# FFN-up epilogue: all main stores write-back on non-last units (write-through only on the last unit)
# baseline (speedup 1.0000x reference)
; __device__ __forceinline__ unsigned pk2(float lo, float hi) { unsigned r; asm volatile("v_cvt_pk_bf16_f32 %0, %1, %2" : "=v"(r) : "v"(lo), "v"(hi)); return r; }
; template <int CTRL> __device__ __forceinline__ float dppz(float x) { return __builtin_bit_cast(float, __builtin_amdgcn_update_dpp(0, __builtin_bit_cast(int, x), CTRL, 0xf, 0xf, true)); }
;     __device__ __forceinline__ void fast(const f32x4 (&acc)[2][2][4][2], const pg8::Unit& u, int wr, int wc, int fr, int fq, RsCache& rsc) const {
;     ...
;             for (int m = 0; m < 4; ++m) {
;                 const int row = rowb + m * 16 + fr; const float s = rsc.tab[ai * 64 + m * 16 + fr]; const f32x2 s2 = (f32x2){s, s};
;                 f32x2 g[4], o[4], v[4];
; #pragma unroll
;                 for (int cp = 0; cp < 4; ++cp) { const int n = cp >> 1, e0 = (cp & 1) * 2;
;                     g[cp] = (f32x2){acc[ai][0][m][n][e0], acc[ai][0][m][n][e0 + 1]} * s2; v[cp] = (f32x2){acc[ai][1][m][n][e0], acc[ai][1][m][n][e0 + 1]} * s2; }
; #pragma unroll
;                 for (int cp = 0; cp < 4; ++cp) {
;                     f32x2 p1 = (f32x2){dppz<0x111>(g[cp].x), dppz<0x111>(g[cp].y)}, p2 = (f32x2){dppz<0x112>(g[cp].x), dppz<0x112>(g[cp].y)};
;                     if (m > 0) { p1 += (f32x2){dppz<0x10F>(gp[cp].x), dppz<0x10F>(gp[cp].y)}; p2 += (f32x2){dppz<0x10E>(gp[cp].x), dppz<0x10E>(gp[cp].y)}; }
;                     const f32x2 gv = bb[cp] + w0[cp] * p2 + w1[cp] * p1 + w2[cp] * g[cp];
;                     const f32x2 ea = gv * (-1.44269504089f);
;                     f32x2 ex; ex.x = __builtin_amdgcn_exp2f(ea.x); ex.y = __builtin_amdgcn_exp2f(ea.y);
;                     const f32x2 dn = ex + 1.0f;
;                     f32x2 rc; rc.x = __builtin_amdgcn_rcpf(dn.x); rc.y = __builtin_amdgcn_rcpf(dn.y);
;                     o[cp] = (gv * rc) * v[cp];
;                 }
;                 if (m > 0 || fr >= 2) { uint4 w; w.x = pk2(o[0].x, o[0].y); w.y = pk2(o[1].x, o[1].y); w.z = pk2(o[2].x, o[2].y); w.w = pk2(o[3].x, o[3].y); *(uint4*)(act + (size_t)row * FH + ch) = w; }
.LBB0_270:
	s_or_b64 exec, exec, s[82:83]
	ds_read_b32 v164, v223 offset:64
	s_mov_b32 s2, 0xbfb8aa3b
	v_readlane_b32 s74, v253, 16
	s_waitcnt lgkmcnt(0)
	v_pk_mul_f32 v[162:163], v[150:151], v[164:165] op_sel_hi:[1,0]
	v_pk_mul_f32 v[168:169], v[142:143], v[164:165] op_sel_hi:[1,0]
	v_pk_mul_f32 v[142:143], v[148:149], v[164:165] op_sel_hi:[1,0]
	v_mov_b32_dpp v148, v162 row_shr:2 row_mask:0xf bank_mask:0xf bound_ctrl:1
	v_mov_b32_dpp v149, v163 row_shr:2 row_mask:0xf bank_mask:0xf bound_ctrl:1
	v_pk_mul_f32 v[150:151], v[152:153], v[164:165] op_sel_hi:[1,0]
	v_pk_mul_f32 v[152:153], v[144:145], v[164:165] op_sel_hi:[1,0]
	v_pk_mul_f32 v[144:145], v[146:147], v[164:165] op_sel_hi:[1,0]
	v_pk_mul_f32 v[138:139], v[138:139], v[164:165] op_sel_hi:[1,0]
	v_pk_mul_f32 v[140:141], v[140:141], v[164:165] op_sel_hi:[1,0]
	v_mov_b32_dpp v146, v162 row_shr:1 row_mask:0xf bank_mask:0xf bound_ctrl:1
	v_mov_b32_dpp v147, v163 row_shr:1 row_mask:0xf bank_mask:0xf bound_ctrl:1
	v_mov_b32_dpp v148, v188 row_shl:14 row_mask:0xf bank_mask:0xf
	v_mov_b32_dpp v149, v189 row_shl:14 row_mask:0xf bank_mask:0xf
	v_mov_b32_dpp v146, v188 row_shl:15 row_mask:0xf bank_mask:0xf
	v_mov_b32_dpp v147, v189 row_shl:15 row_mask:0xf bank_mask:0xf
	v_pk_fma_f32 v[148:149], v[90:91], v[148:149], v[102:103]
	v_mov_b32_dpp v164, v150 row_shr:2 row_mask:0xf bank_mask:0xf bound_ctrl:1
	v_pk_fma_f32 v[146:147], v[94:95], v[146:147], v[148:149]
	v_mov_b32_dpp v165, v151 row_shr:2 row_mask:0xf bank_mask:0xf bound_ctrl:1
	v_pk_fma_f32 v[146:147], v[98:99], v[162:163], v[146:147]
	v_readlane_b32 s75, v253, 17
	v_pk_mul_f32 v[148:149], v[146:147], s[2:3] op_sel_hi:[1,0]
	v_cmp_lt_i32_e32 vcc, 13, v186
	v_exp_f32_e32 v148, v148
	v_exp_f32_e32 v149, v149
	v_lshl_add_u64 v[156:157], v[186:187], 0, -12
	v_pk_add_f32 v[148:149], v[148:149], 1.0 op_sel_hi:[1,0]
	s_nop 0
	v_rcp_f32_e32 v148, v148
	v_rcp_f32_e32 v149, v149
	s_nop 0
	v_pk_mul_f32 v[146:147], v[146:147], v[148:149]
	s_nop 0
	v_pk_mul_f32 v[146:147], v[168:169], v[146:147]
	v_mov_b32_dpp v168, v166 row_shl:15 row_mask:0xf bank_mask:0xf bound_ctrl:1
	v_mov_b32_dpp v169, v167 row_shl:15 row_mask:0xf bank_mask:0xf bound_ctrl:1
	v_mov_b32_dpp v148, v150 row_shr:1 row_mask:0xf bank_mask:0xf bound_ctrl:1
	v_mov_b32_dpp v149, v151 row_shr:1 row_mask:0xf bank_mask:0xf bound_ctrl:1
	v_mov_b32_dpp v164, v166 row_shl:14 row_mask:0xf bank_mask:0xf
	v_mov_b32_dpp v165, v167 row_shl:14 row_mask:0xf bank_mask:0xf
	v_pk_add_f32 v[148:149], v[148:149], v[168:169]
	v_pk_fma_f32 v[164:165], v[92:93], v[164:165], v[104:105]
	v_mov_b32_dpp v166, v160 row_shl:15 row_mask:0xf bank_mask:0xf bound_ctrl:1
	v_pk_fma_f32 v[148:149], v[96:97], v[148:149], v[164:165]
	v_mov_b32_dpp v167, v161 row_shl:15 row_mask:0xf bank_mask:0xf bound_ctrl:1
	v_pk_fma_f32 v[148:149], v[100:101], v[150:151], v[148:149]
	v_mov_b32_dpp v160, v160 row_shl:14 row_mask:0xf bank_mask:0xf bound_ctrl:1
	v_pk_mul_f32 v[164:165], v[148:149], s[2:3] op_sel_hi:[1,0]
	v_mov_b32_dpp v161, v161 row_shl:14 row_mask:0xf bank_mask:0xf bound_ctrl:1
	v_exp_f32_e32 v164, v164
	v_exp_f32_e32 v165, v165
	v_cvt_pk_bf16_f32 v146, v146, v147
	s_nop 0
	v_pk_add_f32 v[164:165], v[164:165], 1.0 op_sel_hi:[1,0]
	s_nop 0
	v_rcp_f32_e32 v164, v164
	v_rcp_f32_e32 v165, v165
	s_nop 0
	v_pk_mul_f32 v[148:149], v[148:149], v[164:165]
	v_mov_b32_dpp v164, v144 row_shr:2 row_mask:0xf bank_mask:0xf bound_ctrl:1
	v_mov_b32_dpp v165, v145 row_shr:2 row_mask:0xf bank_mask:0xf bound_ctrl:1
	v_pk_mul_f32 v[148:149], v[152:153], v[148:149]
	v_mov_b32_dpp v152, v144 row_shr:1 row_mask:0xf bank_mask:0xf bound_ctrl:1
	v_mov_b32_dpp v153, v145 row_shr:1 row_mask:0xf bank_mask:0xf bound_ctrl:1
	v_pk_add_f32 v[160:161], v[164:165], v[160:161]
	v_pk_add_f32 v[152:153], v[152:153], v[166:167]
	v_pk_fma_f32 v[160:161], v[70:71], v[160:161], v[74:75]
	v_mov_b32_dpp v164, v158 row_shl:15 row_mask:0xf bank_mask:0xf bound_ctrl:1
	v_pk_fma_f32 v[152:153], v[58:59], v[152:153], v[160:161]
	v_mov_b32_dpp v165, v159 row_shl:15 row_mask:0xf bank_mask:0xf bound_ctrl:1
	v_pk_fma_f32 v[152:153], v[66:67], v[144:145], v[152:153]
	v_mov_b32_dpp v158, v158 row_shl:14 row_mask:0xf bank_mask:0xf bound_ctrl:1
	v_pk_mul_f32 v[160:161], v[152:153], s[2:3] op_sel_hi:[1,0]
	v_mov_b32_dpp v159, v159 row_shl:14 row_mask:0xf bank_mask:0xf bound_ctrl:1
	v_exp_f32_e32 v160, v160
	v_exp_f32_e32 v161, v161
	v_add_u32_e32 v166, 16, v224
	v_cvt_pk_bf16_f32 v147, v148, v149
	v_pk_add_f32 v[160:161], v[160:161], 1.0 op_sel_hi:[1,0]
	s_nop 0
	v_rcp_f32_e32 v160, v160
	v_rcp_f32_e32 v161, v161
	s_nop 0
	v_pk_mul_f32 v[152:153], v[152:153], v[160:161]
	v_mov_b32_dpp v160, v142 row_shr:2 row_mask:0xf bank_mask:0xf bound_ctrl:1
	v_mov_b32_dpp v161, v143 row_shr:2 row_mask:0xf bank_mask:0xf bound_ctrl:1
	v_pk_mul_f32 v[138:139], v[138:139], v[152:153]
	v_mov_b32_dpp v152, v142 row_shr:1 row_mask:0xf bank_mask:0xf bound_ctrl:1
	v_mov_b32_dpp v153, v143 row_shr:1 row_mask:0xf bank_mask:0xf bound_ctrl:1
	v_pk_add_f32 v[158:159], v[160:161], v[158:159]
	v_pk_add_f32 v[152:153], v[152:153], v[164:165]
	v_pk_fma_f32 v[158:159], v[72:73], v[158:159], v[76:77]
	v_cvt_pk_bf16_f32 v148, v138, v139
	v_mov_b64_e32 v[138:139], s[74:75]
	v_pk_fma_f32 v[152:153], v[60:61], v[152:153], v[158:159]
	s_nop 0
	v_pk_fma_f32 v[152:153], v[68:69], v[142:143], v[152:153]
	s_nop 0
	v_pk_mul_f32 v[158:159], v[152:153], s[2:3] op_sel_hi:[1,0]
	s_nop 0
	v_exp_f32_e32 v158, v158
	v_exp_f32_e32 v159, v159
	s_nop 0
	v_pk_add_f32 v[158:159], v[158:159], 1.0 op_sel_hi:[1,0]
	s_nop 0
	v_rcp_f32_e32 v158, v158
	v_rcp_f32_e32 v159, v159
	s_nop 0
	v_pk_mul_f32 v[152:153], v[152:153], v[158:159]
	s_nop 0
	v_pk_mul_f32 v[140:141], v[140:141], v[152:153]
	v_cvt_pk_bf16_f32 v149, v140, v141
	v_mad_i64_i32 v[140:141], s[74:75], v166, s93, v[138:139]
	v_lshl_add_u64 v[140:141], v[140:141], 0, v[154:155]
	s_cmp_lg_u64 s[4:5], 0
	s_cbranch_scc1 .Lwt_1
	global_store_dwordx4 v[140:141], v[146:149], off
; __device__ __forceinline__ unsigned pk2(float lo, float hi) { unsigned r; asm volatile("v_cvt_pk_bf16_f32 %0, %1, %2" : "=v"(r) : "v"(lo), "v"(hi)); return r; }
; template <int CTRL> __device__ __forceinline__ float dppz(float x) { return __builtin_bit_cast(float, __builtin_amdgcn_update_dpp(0, __builtin_bit_cast(int, x), CTRL, 0xf, 0xf, true)); }
;     __device__ __forceinline__ void fast(const f32x4 (&acc)[2][2][4][2], const pg8::Unit& u, int wr, int wc, int fr, int fq, RsCache& rsc) const {
;     ...
;             for (int m = 0; m < 4; ++m) {
;                 const int row = rowb + m * 16 + fr; const float s = rsc.tab[ai * 64 + m * 16 + fr]; const f32x2 s2 = (f32x2){s, s};
;                 f32x2 g[4], o[4], v[4];
; #pragma unroll
;                 for (int cp = 0; cp < 4; ++cp) { const int n = cp >> 1, e0 = (cp & 1) * 2;
;                     g[cp] = (f32x2){acc[ai][0][m][n][e0], acc[ai][0][m][n][e0 + 1]} * s2; v[cp] = (f32x2){acc[ai][1][m][n][e0], acc[ai][1][m][n][e0 + 1]} * s2; }
; #pragma unroll
;                 for (int cp = 0; cp < 4; ++cp) {
;                     f32x2 p1 = (f32x2){dppz<0x111>(g[cp].x), dppz<0x111>(g[cp].y)}, p2 = (f32x2){dppz<0x112>(g[cp].x), dppz<0x112>(g[cp].y)};
;                     if (m > 0) { p1 += (f32x2){dppz<0x10F>(gp[cp].x), dppz<0x10F>(gp[cp].y)}; p2 += (f32x2){dppz<0x10E>(gp[cp].x), dppz<0x10E>(gp[cp].y)}; }
;                     const f32x2 gv = bb[cp] + w0[cp] * p2 + w1[cp] * p1 + w2[cp] * g[cp];
;                     const f32x2 ea = gv * (-1.44269504089f);
;                     f32x2 ex; ex.x = __builtin_amdgcn_exp2f(ea.x); ex.y = __builtin_amdgcn_exp2f(ea.y);
;                     const f32x2 dn = ex + 1.0f;
;                     f32x2 rc; rc.x = __builtin_amdgcn_rcpf(dn.x); rc.y = __builtin_amdgcn_rcpf(dn.y);
;                     o[cp] = (gv * rc) * v[cp];
;                 }
;                 if (m > 0 || fr >= 2) { uint4 w; w.x = pk2(o[0].x, o[0].y); w.y = pk2(o[1].x, o[1].y); w.z = pk2(o[2].x, o[2].y); w.w = pk2(o[3].x, o[3].y); *(uint4*)(act + (size_t)row * FH + ch) = w; }
.Lwb_1:
	ds_read_b32 v146, v223 offset:128
	s_waitcnt lgkmcnt(0)
	v_pk_mul_f32 v[140:141], v[134:135], v[146:147] op_sel_hi:[1,0]
	v_pk_mul_f32 v[134:135], v[136:137], v[146:147] op_sel_hi:[1,0]
	s_nop 0
	v_mov_b32_dpp v136, v140 row_shr:2 row_mask:0xf bank_mask:0xf bound_ctrl:1
	v_mov_b32_dpp v137, v141 row_shr:2 row_mask:0xf bank_mask:0xf bound_ctrl:1
	v_pk_mul_f32 v[148:149], v[126:127], v[146:147] op_sel_hi:[1,0]
	v_pk_mul_f32 v[128:129], v[128:129], v[146:147] op_sel_hi:[1,0]
	v_pk_mul_f32 v[126:127], v[130:131], v[146:147] op_sel_hi:[1,0]
	v_pk_mul_f32 v[130:131], v[122:123], v[146:147] op_sel_hi:[1,0]
	v_pk_mul_f32 v[122:123], v[132:133], v[146:147] op_sel_hi:[1,0]
	v_pk_mul_f32 v[124:125], v[124:125], v[146:147] op_sel_hi:[1,0]
	v_mov_b32_dpp v132, v140 row_shr:1 row_mask:0xf bank_mask:0xf bound_ctrl:1
	v_mov_b32_dpp v133, v141 row_shr:1 row_mask:0xf bank_mask:0xf bound_ctrl:1
	v_mov_b32_dpp v136, v162 row_shl:14 row_mask:0xf bank_mask:0xf
	v_mov_b32_dpp v137, v163 row_shl:14 row_mask:0xf bank_mask:0xf
	v_mov_b32_dpp v132, v162 row_shl:15 row_mask:0xf bank_mask:0xf
	v_mov_b32_dpp v133, v163 row_shl:15 row_mask:0xf bank_mask:0xf
	v_pk_fma_f32 v[136:137], v[90:91], v[136:137], v[102:103]
	v_mov_b32_dpp v146, v134 row_shr:2 row_mask:0xf bank_mask:0xf bound_ctrl:1
	v_pk_fma_f32 v[132:133], v[94:95], v[132:133], v[136:137]
	v_mov_b32_dpp v147, v135 row_shr:2 row_mask:0xf bank_mask:0xf bound_ctrl:1
	v_pk_fma_f32 v[132:133], v[98:99], v[140:141], v[132:133]
	s_nop 0
	v_pk_mul_f32 v[136:137], v[132:133], s[2:3] op_sel_hi:[1,0]
	s_nop 0
	v_exp_f32_e32 v136, v136
	v_exp_f32_e32 v137, v137
	s_nop 0
	v_pk_add_f32 v[136:137], v[136:137], 1.0 op_sel_hi:[1,0]
	s_nop 0
	v_rcp_f32_e32 v136, v136
	v_rcp_f32_e32 v137, v137
	s_nop 0
	v_pk_mul_f32 v[132:133], v[132:133], v[136:137]
	s_nop 0
	v_pk_mul_f32 v[132:133], v[148:149], v[132:133]
	v_mov_b32_dpp v148, v150 row_shl:15 row_mask:0xf bank_mask:0xf bound_ctrl:1
	v_mov_b32_dpp v149, v151 row_shl:15 row_mask:0xf bank_mask:0xf bound_ctrl:1
	v_mov_b32_dpp v136, v134 row_shr:1 row_mask:0xf bank_mask:0xf bound_ctrl:1
	v_mov_b32_dpp v137, v135 row_shr:1 row_mask:0xf bank_mask:0xf bound_ctrl:1
	v_mov_b32_dpp v146, v150 row_shl:14 row_mask:0xf bank_mask:0xf
	v_mov_b32_dpp v147, v151 row_shl:14 row_mask:0xf bank_mask:0xf
	v_pk_add_f32 v[136:137], v[136:137], v[148:149]
	v_pk_fma_f32 v[146:147], v[92:93], v[146:147], v[104:105]
	v_mov_b32_dpp v148, v144 row_shl:15 row_mask:0xf bank_mask:0xf bound_ctrl:1
	v_pk_fma_f32 v[136:137], v[96:97], v[136:137], v[146:147]
	v_mov_b32_dpp v149, v145 row_shl:15 row_mask:0xf bank_mask:0xf bound_ctrl:1
	v_pk_fma_f32 v[136:137], v[100:101], v[134:135], v[136:137]
	v_mov_b32_dpp v144, v144 row_shl:14 row_mask:0xf bank_mask:0xf bound_ctrl:1
	v_pk_mul_f32 v[146:147], v[136:137], s[2:3] op_sel_hi:[1,0]
	v_mov_b32_dpp v145, v145 row_shl:14 row_mask:0xf bank_mask:0xf bound_ctrl:1
	v_exp_f32_e32 v146, v146
	v_exp_f32_e32 v147, v147
	s_nop 0
	v_pk_add_f32 v[146:147], v[146:147], 1.0 op_sel_hi:[1,0]
	s_nop 0
	v_rcp_f32_e32 v146, v146
	v_rcp_f32_e32 v147, v147
	s_nop 0
	v_pk_mul_f32 v[136:137], v[136:137], v[146:147]
	v_mov_b32_dpp v146, v126 row_shr:2 row_mask:0xf bank_mask:0xf bound_ctrl:1
	v_mov_b32_dpp v147, v127 row_shr:2 row_mask:0xf bank_mask:0xf bound_ctrl:1
	v_pk_mul_f32 v[136:137], v[128:129], v[136:137]
	v_mov_b32_dpp v128, v126 row_shr:1 row_mask:0xf bank_mask:0xf bound_ctrl:1
	v_mov_b32_dpp v129, v127 row_shr:1 row_mask:0xf bank_mask:0xf bound_ctrl:1
	v_pk_add_f32 v[144:145], v[146:147], v[144:145]
	v_pk_add_f32 v[128:129], v[128:129], v[148:149]
	v_pk_fma_f32 v[144:145], v[70:71], v[144:145], v[74:75]
	v_mov_b32_dpp v146, v142 row_shl:15 row_mask:0xf bank_mask:0xf bound_ctrl:1
	v_pk_fma_f32 v[128:129], v[58:59], v[128:129], v[144:145]
	v_mov_b32_dpp v147, v143 row_shl:15 row_mask:0xf bank_mask:0xf bound_ctrl:1
	v_pk_fma_f32 v[128:129], v[66:67], v[126:127], v[128:129]
	v_mov_b32_dpp v142, v142 row_shl:14 row_mask:0xf bank_mask:0xf bound_ctrl:1
	v_pk_mul_f32 v[144:145], v[128:129], s[2:3] op_sel_hi:[1,0]
	v_mov_b32_dpp v143, v143 row_shl:14 row_mask:0xf bank_mask:0xf bound_ctrl:1
	v_exp_f32_e32 v144, v144
	v_exp_f32_e32 v145, v145
	v_add_u32_e32 v148, 32, v224
	v_pk_add_f32 v[144:145], v[144:145], 1.0 op_sel_hi:[1,0]
	s_nop 0
	v_rcp_f32_e32 v144, v144
	v_rcp_f32_e32 v145, v145
	s_nop 0
	v_pk_mul_f32 v[128:129], v[128:129], v[144:145]
	v_mov_b32_dpp v144, v122 row_shr:2 row_mask:0xf bank_mask:0xf bound_ctrl:1
	v_mov_b32_dpp v145, v123 row_shr:2 row_mask:0xf bank_mask:0xf bound_ctrl:1
	v_pk_mul_f32 v[130:131], v[130:131], v[128:129]
	v_mov_b32_dpp v128, v122 row_shr:1 row_mask:0xf bank_mask:0xf bound_ctrl:1
	v_mov_b32_dpp v129, v123 row_shr:1 row_mask:0xf bank_mask:0xf bound_ctrl:1
	v_pk_add_f32 v[142:143], v[144:145], v[142:143]
	v_pk_add_f32 v[128:129], v[128:129], v[146:147]
	v_pk_fma_f32 v[142:143], v[72:73], v[142:143], v[76:77]
	s_nop 0
	v_pk_fma_f32 v[128:129], v[60:61], v[128:129], v[142:143]
	s_nop 0
	v_pk_fma_f32 v[128:129], v[68:69], v[122:123], v[128:129]
	s_nop 0
	v_pk_mul_f32 v[142:143], v[128:129], s[2:3] op_sel_hi:[1,0]
	s_nop 0
	v_exp_f32_e32 v142, v142
	v_exp_f32_e32 v143, v143
	s_nop 0
	v_pk_add_f32 v[142:143], v[142:143], 1.0 op_sel_hi:[1,0]
	s_nop 0
	v_rcp_f32_e32 v142, v142
	v_rcp_f32_e32 v143, v143
	s_nop 0
	v_pk_mul_f32 v[128:129], v[128:129], v[142:143]
	s_nop 0
	v_pk_mul_f32 v[124:125], v[124:125], v[128:129]
	v_cvt_pk_bf16_f32 v128, v132, v133
	v_cvt_pk_bf16_f32 v129, v136, v137
	v_cvt_pk_bf16_f32 v130, v130, v131
	v_cvt_pk_bf16_f32 v131, v124, v125
	v_mad_i64_i32 v[124:125], s[74:75], v148, s93, v[138:139]
	v_lshl_add_u64 v[124:125], v[124:125], 0, v[154:155]
	s_cmp_lg_u64 s[4:5], 0
	s_cbranch_scc1 .Lwt_2
	global_store_dwordx4 v[124:125], v[128:131], off
; __device__ __forceinline__ unsigned pk2(float lo, float hi) { unsigned r; asm volatile("v_cvt_pk_bf16_f32 %0, %1, %2" : "=v"(r) : "v"(lo), "v"(hi)); return r; }
; template <int CTRL> __device__ __forceinline__ float dppz(float x) { return __builtin_bit_cast(float, __builtin_amdgcn_update_dpp(0, __builtin_bit_cast(int, x), CTRL, 0xf, 0xf, true)); }
;     __device__ __forceinline__ void fast(const f32x4 (&acc)[2][2][4][2], const pg8::Unit& u, int wr, int wc, int fr, int fq, RsCache& rsc) const {
;     ...
;             for (int m = 0; m < 4; ++m) {
;                 const int row = rowb + m * 16 + fr; const float s = rsc.tab[ai * 64 + m * 16 + fr]; const f32x2 s2 = (f32x2){s, s};
;                 f32x2 g[4], o[4], v[4];
; #pragma unroll
;                 for (int cp = 0; cp < 4; ++cp) { const int n = cp >> 1, e0 = (cp & 1) * 2;
;                     g[cp] = (f32x2){acc[ai][0][m][n][e0], acc[ai][0][m][n][e0 + 1]} * s2; v[cp] = (f32x2){acc[ai][1][m][n][e0], acc[ai][1][m][n][e0 + 1]} * s2; }
; #pragma unroll
;                 for (int cp = 0; cp < 4; ++cp) {
;                     f32x2 p1 = (f32x2){dppz<0x111>(g[cp].x), dppz<0x111>(g[cp].y)}, p2 = (f32x2){dppz<0x112>(g[cp].x), dppz<0x112>(g[cp].y)};
;                     if (m > 0) { p1 += (f32x2){dppz<0x10F>(gp[cp].x), dppz<0x10F>(gp[cp].y)}; p2 += (f32x2){dppz<0x10E>(gp[cp].x), dppz<0x10E>(gp[cp].y)}; }
;                     const f32x2 gv = bb[cp] + w0[cp] * p2 + w1[cp] * p1 + w2[cp] * g[cp];
;                     const f32x2 ea = gv * (-1.44269504089f);
;                     f32x2 ex; ex.x = __builtin_amdgcn_exp2f(ea.x); ex.y = __builtin_amdgcn_exp2f(ea.y);
;                     const f32x2 dn = ex + 1.0f;
;                     f32x2 rc; rc.x = __builtin_amdgcn_rcpf(dn.x); rc.y = __builtin_amdgcn_rcpf(dn.y);
;                     o[cp] = (gv * rc) * v[cp];
;                 }
;                 if (m > 0 || fr >= 2) { uint4 w; w.x = pk2(o[0].x, o[0].y); w.y = pk2(o[1].x, o[1].y); w.z = pk2(o[2].x, o[2].y); w.w = pk2(o[3].x, o[3].y); *(uint4*)(act + (size_t)row * FH + ch) = w; }
.Lwb_2:
	ds_read_b32 v124, v223 offset:192
	s_waitcnt lgkmcnt(0)
	v_pk_mul_f32 v[118:119], v[118:119], v[124:125] op_sel_hi:[1,0]
	v_pk_mul_f32 v[128:129], v[110:111], v[124:125] op_sel_hi:[1,0]
	v_pk_mul_f32 v[110:111], v[120:121], v[124:125] op_sel_hi:[1,0]
	v_pk_mul_f32 v[120:121], v[112:113], v[124:125] op_sel_hi:[1,0]
	v_pk_mul_f32 v[112:113], v[114:115], v[124:125] op_sel_hi:[1,0]
	v_pk_mul_f32 v[114:115], v[106:107], v[124:125] op_sel_hi:[1,0]
	v_pk_mul_f32 v[106:107], v[116:117], v[124:125] op_sel_hi:[1,0]
	v_pk_mul_f32 v[108:109], v[108:109], v[124:125] op_sel_hi:[1,0]
	v_mov_b32_dpp v124, v118 row_shr:2 row_mask:0xf bank_mask:0xf bound_ctrl:1
	v_mov_b32_dpp v125, v119 row_shr:2 row_mask:0xf bank_mask:0xf bound_ctrl:1
	v_mov_b32_dpp v116, v118 row_shr:1 row_mask:0xf bank_mask:0xf bound_ctrl:1
	v_mov_b32_dpp v117, v119 row_shr:1 row_mask:0xf bank_mask:0xf bound_ctrl:1
	v_mov_b32_dpp v124, v140 row_shl:14 row_mask:0xf bank_mask:0xf
	v_mov_b32_dpp v125, v141 row_shl:14 row_mask:0xf bank_mask:0xf
	v_mov_b32_dpp v116, v140 row_shl:15 row_mask:0xf bank_mask:0xf
	v_mov_b32_dpp v117, v141 row_shl:15 row_mask:0xf bank_mask:0xf
	v_pk_fma_f32 v[124:125], v[90:91], v[124:125], v[102:103]
	v_pk_fma_f32 v[116:117], v[94:95], v[116:117], v[124:125]
	v_pk_fma_f32 v[116:117], v[98:99], v[118:119], v[116:117]
	v_pk_mul_f32 v[124:125], v[116:117], s[2:3] op_sel_hi:[1,0]
	v_exp_f32_e32 v124, v124
	v_exp_f32_e32 v125, v125
	s_nop 0
	v_pk_add_f32 v[124:125], v[124:125], 1.0 op_sel_hi:[1,0]
	s_nop 0
	v_rcp_f32_e32 v124, v124
	v_rcp_f32_e32 v125, v125
	s_nop 0
	v_pk_mul_f32 v[116:117], v[116:117], v[124:125]
	s_nop 0
	v_pk_mul_f32 v[116:117], v[128:129], v[116:117]
	v_mov_b32_dpp v128, v110 row_shr:2 row_mask:0xf bank_mask:0xf bound_ctrl:1
	v_mov_b32_dpp v129, v111 row_shr:2 row_mask:0xf bank_mask:0xf bound_ctrl:1
	v_mov_b32_dpp v124, v110 row_shr:1 row_mask:0xf bank_mask:0xf bound_ctrl:1
	v_mov_b32_dpp v125, v111 row_shr:1 row_mask:0xf bank_mask:0xf bound_ctrl:1
	v_mov_b32_dpp v128, v134 row_shl:14 row_mask:0xf bank_mask:0xf
	v_mov_b32_dpp v129, v135 row_shl:14 row_mask:0xf bank_mask:0xf
	v_mov_b32_dpp v124, v134 row_shl:15 row_mask:0xf bank_mask:0xf
	v_mov_b32_dpp v125, v135 row_shl:15 row_mask:0xf bank_mask:0xf
	v_pk_fma_f32 v[128:129], v[92:93], v[128:129], v[104:105]
	v_mov_b32_dpp v130, v126 row_shl:15 row_mask:0xf bank_mask:0xf bound_ctrl:1
	v_pk_fma_f32 v[124:125], v[96:97], v[124:125], v[128:129]
	v_mov_b32_dpp v131, v127 row_shl:15 row_mask:0xf bank_mask:0xf bound_ctrl:1
	v_pk_fma_f32 v[124:125], v[100:101], v[110:111], v[124:125]
	v_mov_b32_dpp v126, v126 row_shl:14 row_mask:0xf bank_mask:0xf bound_ctrl:1
	v_pk_mul_f32 v[128:129], v[124:125], s[2:3] op_sel_hi:[1,0]
	v_mov_b32_dpp v127, v127 row_shl:14 row_mask:0xf bank_mask:0xf bound_ctrl:1
	v_exp_f32_e32 v128, v128
	v_exp_f32_e32 v129, v129
	s_nop 0
	v_pk_add_f32 v[128:129], v[128:129], 1.0 op_sel_hi:[1,0]
	s_nop 0
	v_rcp_f32_e32 v128, v128
	v_rcp_f32_e32 v129, v129
	s_nop 0
	v_pk_mul_f32 v[124:125], v[124:125], v[128:129]
	v_mov_b32_dpp v128, v112 row_shr:2 row_mask:0xf bank_mask:0xf bound_ctrl:1
	v_mov_b32_dpp v129, v113 row_shr:2 row_mask:0xf bank_mask:0xf bound_ctrl:1
	v_pk_mul_f32 v[120:121], v[120:121], v[124:125]
	v_mov_b32_dpp v124, v112 row_shr:1 row_mask:0xf bank_mask:0xf bound_ctrl:1
	v_mov_b32_dpp v125, v113 row_shr:1 row_mask:0xf bank_mask:0xf bound_ctrl:1
	v_pk_add_f32 v[126:127], v[128:129], v[126:127]
	v_pk_add_f32 v[124:125], v[124:125], v[130:131]
	v_pk_fma_f32 v[126:127], v[70:71], v[126:127], v[74:75]
	v_mov_b32_dpp v128, v122 row_shl:15 row_mask:0xf bank_mask:0xf bound_ctrl:1
	v_pk_fma_f32 v[124:125], v[58:59], v[124:125], v[126:127]
	v_mov_b32_dpp v129, v123 row_shl:15 row_mask:0xf bank_mask:0xf bound_ctrl:1
	v_pk_fma_f32 v[124:125], v[66:67], v[112:113], v[124:125]
	v_mov_b32_dpp v122, v122 row_shl:14 row_mask:0xf bank_mask:0xf bound_ctrl:1
	v_pk_mul_f32 v[126:127], v[124:125], s[2:3] op_sel_hi:[1,0]
	v_mov_b32_dpp v123, v123 row_shl:14 row_mask:0xf bank_mask:0xf bound_ctrl:1
	v_exp_f32_e32 v126, v126
	v_exp_f32_e32 v127, v127
	v_add_u32_e32 v130, 48, v224
	v_pk_add_f32 v[126:127], v[126:127], 1.0 op_sel_hi:[1,0]
	s_nop 0
	v_rcp_f32_e32 v126, v126
	v_rcp_f32_e32 v127, v127
	s_nop 0
	v_pk_mul_f32 v[124:125], v[124:125], v[126:127]
	v_mov_b32_dpp v126, v106 row_shr:2 row_mask:0xf bank_mask:0xf bound_ctrl:1
	v_mov_b32_dpp v127, v107 row_shr:2 row_mask:0xf bank_mask:0xf bound_ctrl:1
	v_pk_mul_f32 v[124:125], v[114:115], v[124:125]
	v_mov_b32_dpp v114, v106 row_shr:1 row_mask:0xf bank_mask:0xf bound_ctrl:1
	v_mov_b32_dpp v115, v107 row_shr:1 row_mask:0xf bank_mask:0xf bound_ctrl:1
	v_pk_add_f32 v[122:123], v[126:127], v[122:123]
	v_pk_add_f32 v[114:115], v[114:115], v[128:129]
	v_pk_fma_f32 v[122:123], v[72:73], v[122:123], v[76:77]
	s_nop 0
	v_pk_fma_f32 v[114:115], v[60:61], v[114:115], v[122:123]
	s_nop 0
	v_pk_fma_f32 v[114:115], v[68:69], v[106:107], v[114:115]
	s_nop 0
	v_pk_mul_f32 v[122:123], v[114:115], s[2:3] op_sel_hi:[1,0]
	s_nop 0
	v_exp_f32_e32 v122, v122
	v_exp_f32_e32 v123, v123
	s_nop 0
	v_pk_add_f32 v[122:123], v[122:123], 1.0 op_sel_hi:[1,0]
	s_nop 0
	v_rcp_f32_e32 v122, v122
	v_rcp_f32_e32 v123, v123
	s_nop 0
	v_pk_mul_f32 v[114:115], v[114:115], v[122:123]
	s_nop 0
	v_pk_mul_f32 v[108:109], v[108:109], v[114:115]
	v_cvt_pk_bf16_f32 v114, v116, v117
	v_cvt_pk_bf16_f32 v115, v120, v121
	v_cvt_pk_bf16_f32 v116, v124, v125
	s_nop 0
	v_cvt_pk_bf16_f32 v117, v108, v109
	v_mad_i64_i32 v[108:109], s[74:75], v130, s93, v[138:139]
	v_lshl_add_u64 v[108:109], v[108:109], 0, v[154:155]
	s_cmp_lg_u64 s[4:5], 0
	s_cbranch_scc1 .Lwt_3
	global_store_dwordx4 v[108:109], v[114:117], off
;     __device__ __forceinline__ void fast(const f32x4 (&acc)[2][2][4][2], const pg8::Unit& u, int wr, int wc, int fr, int fq, RsCache& rsc) const {
;     ...
;                 const int row = rowb + m * 16 + fr; const float s = rsc.tab[ai * 64 + m * 16 + fr]; const f32x2 s2 = (f32x2){s, s};
;                 f32x2 g[4], o[4], v[4];
; #pragma unroll
;                 for (int cp = 0; cp < 4; ++cp) { const int n = cp >> 1, e0 = (cp & 1) * 2;
;                     g[cp] = (f32x2){acc[ai][0][m][n][e0], acc[ai][0][m][n][e0 + 1]} * s2; v[cp] = (f32x2){acc[ai][1][m][n][e0], acc[ai][1][m][n][e0 + 1]} * s2; }
; #pragma unroll
;                 for (int cp = 0; cp < 4; ++cp) {
;                     f32x2 p1 = (f32x2){dppz<0x111>(g[cp].x), dppz<0x111>(g[cp].y)}, p2 = (f32x2){dppz<0x112>(g[cp].x), dppz<0x112>(g[cp].y)};
;                     if (m > 0) { p1 += (f32x2){dppz<0x10F>(gp[cp].x), dppz<0x10F>(gp[cp].y)}; p2 += (f32x2){dppz<0x10E>(gp[cp].x), dppz<0x10E>(gp[cp].y)}; }
;                     const f32x2 gv = bb[cp] + w0[cp] * p2 + w1[cp] * p1 + w2[cp] * g[cp];
;                     const f32x2 ea = gv * (-1.44269504089f);
;                     f32x2 ex; ex.x = __builtin_amdgcn_exp2f(ea.x); ex.y = __builtin_amdgcn_exp2f(ea.y);
;                     const f32x2 dn = ex + 1.0f;
;                     f32x2 rc; rc.x = __builtin_amdgcn_rcpf(dn.x); rc.y = __builtin_amdgcn_rcpf(dn.y);
;                     o[cp] = (gv * rc) * v[cp];
;                 }
;                 if (m > 0 || fr >= 2) { uint4 w; w.x = pk2(o[0].x, o[0].y); w.y = pk2(o[1].x, o[1].y); w.z = pk2(o[2].x, o[2].y); w.w = pk2(o[3].x, o[3].y); *(uint4*)(act + (size_t)row * FH + ch) = w; }
;                 if (m == 0 && fr < 2) { uint4 w; w.x = pk2(g[0].x, g[0].y); w.y = pk2(g[1].x, g[1].y); w.z = pk2(g[2].x, g[2].y); w.w = pk2(g[3].x, g[3].y); *(uint4*)(sideg + ((size_t)blk * 4 + fr) * FH + ch) = w;
;                     uint4 q; q.x = pk2(v[0].x, v[0].y); q.y = pk2(v[1].x, v[1].y); q.z = pk2(v[2].x, v[2].y); q.w = pk2(v[3].x, v[3].y); *(uint4*)(sidev + ((size_t)blk * 2 + fr) * FH + ch) = q; }
;                 if (m == 3 && fr >= 14) { uint4 w; w.x = pk2(g[0].x, g[0].y); w.y = pk2(g[1].x, g[1].y); w.z = pk2(g[2].x, g[2].y); w.w = pk2(g[3].x, g[3].y); *(uint4*)(sideg + ((size_t)blk * 4 + 2 + (fr - 14)) * FH + ch) = w; }
.Lwb_3:
	s_and_saveexec_b64 s[82:83], vcc
	s_cbranch_execz .LBB0_272
	v_lshl_add_u64 v[114:115], s[0:1], 0, v[156:157]
	v_readlane_b32 s0, v254, 1
	v_readlane_b32 s1, v254, 2
	v_cvt_pk_bf16_f32 v108, v118, v119
	v_cvt_pk_bf16_f32 v109, v110, v111
	v_cvt_pk_bf16_f32 v110, v112, v113
	v_cvt_pk_bf16_f32 v111, v106, v107
	s_nop 1
	v_mov_b64_e32 v[106:107], s[0:1]
	v_mad_u64_u32 v[106:107], s[0:1], v114, s93, v[106:107]
	v_mad_i32_i24 v107, v115, s93, v107
	v_lshl_add_u64 v[106:107], v[184:185], 1, v[106:107]
	s_cmp_lg_u64 s[4:5], 0
	s_cbranch_scc1 .Lwt_4
	global_store_dwordx4 v[106:107], v[108:111], off
.Lwb_4:
.LBB0_272:
	s_or_b64 exec, exec, s[82:83]
	ds_read_b32 v110, v223 offset:256
	s_add_i32 s2, s3, 0x80
	v_add_u32_e32 v122, s2, v186
	s_waitcnt lgkmcnt(0)
	v_pk_mul_f32 v[106:107], v[86:87], v[110:111] op_sel_hi:[1,0]
	v_pk_mul_f32 v[108:109], v[78:79], v[110:111] op_sel_hi:[1,0]
	v_pk_mul_f32 v[86:87], v[88:89], v[110:111] op_sel_hi:[1,0]
	v_pk_mul_f32 v[78:79], v[82:83], v[110:111] op_sel_hi:[1,0]
	v_pk_mul_f32 v[82:83], v[62:63], v[110:111] op_sel_hi:[1,0]
	v_pk_mul_f32 v[62:63], v[84:85], v[110:111] op_sel_hi:[1,0]
	v_pk_mul_f32 v[80:81], v[80:81], v[110:111] op_sel_hi:[1,0]
	v_pk_mul_f32 v[64:65], v[64:65], v[110:111] op_sel_hi:[1,0]
	v_mov_b32_dpp v110, v106 row_shr:1 row_mask:0xf bank_mask:0xf bound_ctrl:1
	v_mov_b32_dpp v111, v107 row_shr:1 row_mask:0xf bank_mask:0xf bound_ctrl:1
	v_mov_b32_dpp v112, v106 row_shr:2 row_mask:0xf bank_mask:0xf bound_ctrl:1
	v_mov_b32_dpp v113, v107 row_shr:2 row_mask:0xf bank_mask:0xf bound_ctrl:1
	v_mov_b32_dpp v114, v86 row_shr:1 row_mask:0xf bank_mask:0xf bound_ctrl:1
	v_mov_b32_dpp v115, v87 row_shr:1 row_mask:0xf bank_mask:0xf bound_ctrl:1
	v_mov_b32_dpp v116, v86 row_shr:2 row_mask:0xf bank_mask:0xf bound_ctrl:1
	v_mov_b32_dpp v117, v87 row_shr:2 row_mask:0xf bank_mask:0xf bound_ctrl:1
	v_mov_b32_dpp v118, v78 row_shr:1 row_mask:0xf bank_mask:0xf bound_ctrl:1
	v_mov_b32_dpp v119, v79 row_shr:1 row_mask:0xf bank_mask:0xf bound_ctrl:1
	v_mov_b32_dpp v120, v78 row_shr:2 row_mask:0xf bank_mask:0xf bound_ctrl:1
	v_mov_b32_dpp v121, v79 row_shr:2 row_mask:0xf bank_mask:0xf bound_ctrl:1
	v_mov_b32_dpp v84, v62 row_shr:1 row_mask:0xf bank_mask:0xf bound_ctrl:1
	v_mov_b32_dpp v85, v63 row_shr:1 row_mask:0xf bank_mask:0xf bound_ctrl:1
	v_mov_b32_dpp v88, v62 row_shr:2 row_mask:0xf bank_mask:0xf bound_ctrl:1
	v_mov_b32_dpp v89, v63 row_shr:2 row_mask:0xf bank_mask:0xf bound_ctrl:1
	s_and_saveexec_b64 s[0:1], s[6:7]
	s_cbranch_execz .LBB0_274
	v_pk_fma_f32 v[112:113], v[90:91], v[112:113], v[102:103]
	v_pk_fma_f32 v[88:89], v[72:73], v[88:89], v[76:77]
	v_pk_fma_f32 v[120:121], v[70:71], v[120:121], v[74:75]
	v_pk_fma_f32 v[116:117], v[92:93], v[116:117], v[104:105]
	v_pk_fma_f32 v[110:111], v[94:95], v[110:111], v[112:113]
	v_pk_fma_f32 v[84:85], v[60:61], v[84:85], v[88:89]
	v_pk_fma_f32 v[118:119], v[58:59], v[118:119], v[120:121]
	s_mov_b32 s6, 0xbfb8aa3b
	v_pk_fma_f32 v[114:115], v[96:97], v[114:115], v[116:117]
	v_pk_fma_f32 v[110:111], v[98:99], v[106:107], v[110:111]
	v_pk_fma_f32 v[84:85], v[68:69], v[62:63], v[84:85]
	v_pk_fma_f32 v[118:119], v[66:67], v[78:79], v[118:119]
	v_pk_fma_f32 v[114:115], v[100:101], v[86:87], v[114:115]
	v_pk_mul_f32 v[112:113], v[110:111], s[6:7] op_sel_hi:[1,0]
	v_pk_mul_f32 v[88:89], v[84:85], s[6:7] op_sel_hi:[1,0]
	v_pk_mul_f32 v[120:121], v[118:119], s[6:7] op_sel_hi:[1,0]
	v_pk_mul_f32 v[116:117], v[114:115], s[6:7] op_sel_hi:[1,0]
	v_exp_f32_e32 v112, v112
	v_exp_f32_e32 v113, v113
	v_exp_f32_e32 v88, v88
	v_exp_f32_e32 v89, v89
	v_exp_f32_e32 v120, v120
	v_exp_f32_e32 v121, v121
	v_exp_f32_e32 v116, v116
	v_exp_f32_e32 v117, v117
	v_pk_add_f32 v[112:113], v[112:113], 1.0 op_sel_hi:[1,0]
	v_pk_add_f32 v[88:89], v[88:89], 1.0 op_sel_hi:[1,0]
	v_pk_add_f32 v[120:121], v[120:121], 1.0 op_sel_hi:[1,0]
	v_pk_add_f32 v[116:117], v[116:117], 1.0 op_sel_hi:[1,0]
	v_rcp_f32_e32 v112, v112
	v_rcp_f32_e32 v113, v113
	v_rcp_f32_e32 v88, v88
	v_rcp_f32_e32 v89, v89
	v_rcp_f32_e32 v120, v120
	v_rcp_f32_e32 v121, v121
	v_rcp_f32_e32 v116, v116
	v_rcp_f32_e32 v117, v117
	v_pk_mul_f32 v[110:111], v[110:111], v[112:113]
	v_pk_mul_f32 v[84:85], v[84:85], v[88:89]
	v_readlane_b32 s6, v253, 16
	v_pk_mul_f32 v[118:119], v[118:119], v[120:121]
	v_pk_mul_f32 v[114:115], v[114:115], v[116:117]
	v_pk_mul_f32 v[110:111], v[108:109], v[110:111]
	v_pk_mul_f32 v[84:85], v[64:65], v[84:85]
	v_readlane_b32 s7, v253, 17
	v_pk_mul_f32 v[118:119], v[82:83], v[118:119]
	v_pk_mul_f32 v[114:115], v[80:81], v[114:115]
	v_cvt_pk_bf16_f32 v110, v110, v111
	s_nop 0
	v_cvt_pk_bf16_f32 v111, v114, v115
	v_cvt_pk_bf16_f32 v112, v118, v119
	v_cvt_pk_bf16_f32 v113, v84, v85
	v_mov_b64_e32 v[84:85], s[6:7]
	v_mad_i64_i32 v[84:85], s[6:7], v122, s93, v[84:85]
	v_lshl_add_u64 v[84:85], v[184:185], 1, v[84:85]
	s_cmp_lg_u64 s[4:5], 0
	s_cbranch_scc1 .Lwt_5
	global_store_dwordx4 v[84:85], v[110:113], off
.Lwb_5:
.LBB0_274:
	s_or_b64 exec, exec, s[0:1]
	s_ashr_i32 s0, s2, 6
	s_ashr_i32 s1, s0, 31
	s_lshl_b64 s[6:7], s[0:1], 2
	s_and_saveexec_b64 s[82:83], s[8:9]
	s_cbranch_execz .LBB0_276
	v_lshl_add_u64 v[84:85], s[6:7], 0, v[186:187]
	s_lshl_b64 s[0:1], s[0:1], 1
	v_mov_b32_e32 v88, s1
	v_subrev_co_u32_e64 v114, s[0:1], s0, v84
	v_cvt_pk_bf16_f32 v110, v106, v107
	v_cvt_pk_bf16_f32 v111, v86, v87
	v_cvt_pk_bf16_f32 v112, v78, v79
	v_cvt_pk_bf16_f32 v113, v62, v63
	s_nop 1
	v_subb_co_u32_e64 v115, s[0:1], v85, v88, s[0:1]
	v_readlane_b32 s0, v254, 1
	v_readlane_b32 s1, v254, 2
	s_nop 1
	v_mov_b64_e32 v[88:89], s[0:1]
	v_mad_u64_u32 v[88:89], s[0:1], v84, s93, v[88:89]
	v_mad_i32_i24 v89, v85, s93, v89
	v_readlane_b32 s0, v254, 15
	v_lshl_add_u64 v[84:85], v[88:89], 0, v[154:155]
	v_readlane_b32 s1, v254, 16
	s_cmp_lg_u64 s[4:5], 0
	s_cbranch_scc1 .Lwt_6
	global_store_dwordx4 v[84:85], v[110:113], off
;     __device__ __forceinline__ void fast(const f32x4 (&acc)[2][2][4][2], const pg8::Unit& u, int wr, int wc, int fr, int fq, RsCache& rsc) const {
;     ...
;                 const int row = rowb + m * 16 + fr; const float s = rsc.tab[ai * 64 + m * 16 + fr]; const f32x2 s2 = (f32x2){s, s};
;                 f32x2 g[4], o[4], v[4];
; #pragma unroll
;                 for (int cp = 0; cp < 4; ++cp) { const int n = cp >> 1, e0 = (cp & 1) * 2;
;                     g[cp] = (f32x2){acc[ai][0][m][n][e0], acc[ai][0][m][n][e0 + 1]} * s2; v[cp] = (f32x2){acc[ai][1][m][n][e0], acc[ai][1][m][n][e0 + 1]} * s2; }
; #pragma unroll
;                 for (int cp = 0; cp < 4; ++cp) {
;                     f32x2 p1 = (f32x2){dppz<0x111>(g[cp].x), dppz<0x111>(g[cp].y)}, p2 = (f32x2){dppz<0x112>(g[cp].x), dppz<0x112>(g[cp].y)};
;                     if (m > 0) { p1 += (f32x2){dppz<0x10F>(gp[cp].x), dppz<0x10F>(gp[cp].y)}; p2 += (f32x2){dppz<0x10E>(gp[cp].x), dppz<0x10E>(gp[cp].y)}; }
;                     const f32x2 gv = bb[cp] + w0[cp] * p2 + w1[cp] * p1 + w2[cp] * g[cp];
;                     const f32x2 ea = gv * (-1.44269504089f);
;                     f32x2 ex; ex.x = __builtin_amdgcn_exp2f(ea.x); ex.y = __builtin_amdgcn_exp2f(ea.y);
;                     const f32x2 dn = ex + 1.0f;
;                     f32x2 rc; rc.x = __builtin_amdgcn_rcpf(dn.x); rc.y = __builtin_amdgcn_rcpf(dn.y);
;                     o[cp] = (gv * rc) * v[cp];
;                 }
;                 if (m > 0 || fr >= 2) { uint4 w; w.x = pk2(o[0].x, o[0].y); w.y = pk2(o[1].x, o[1].y); w.z = pk2(o[2].x, o[2].y); w.w = pk2(o[3].x, o[3].y); *(uint4*)(act + (size_t)row * FH + ch) = w; }
;                 if (m == 0 && fr < 2) { uint4 w; w.x = pk2(g[0].x, g[0].y); w.y = pk2(g[1].x, g[1].y); w.z = pk2(g[2].x, g[2].y); w.w = pk2(g[3].x, g[3].y); *(uint4*)(sideg + ((size_t)blk * 4 + fr) * FH + ch) = w;
;                     uint4 q; q.x = pk2(v[0].x, v[0].y); q.y = pk2(v[1].x, v[1].y); q.z = pk2(v[2].x, v[2].y); q.w = pk2(v[3].x, v[3].y); *(uint4*)(sidev + ((size_t)blk * 2 + fr) * FH + ch) = q; }
;                 if (m == 3 && fr >= 14) { uint4 w; w.x = pk2(g[0].x, g[0].y); w.y = pk2(g[1].x, g[1].y); w.z = pk2(g[2].x, g[2].y); w.w = pk2(g[3].x, g[3].y); *(uint4*)(sideg + ((size_t)blk * 4 + 2 + (fr - 14)) * FH + ch) = w; }
.Lwb_6:
	v_cvt_pk_bf16_f32 v108, v108, v109
	v_cvt_pk_bf16_f32 v109, v80, v81
	s_nop 1
	v_cvt_pk_bf16_f32 v110, v82, v83
	v_cvt_pk_bf16_f32 v111, v64, v65
	v_mov_b64_e32 v[64:65], s[0:1]
	v_mad_u64_u32 v[64:65], s[0:1], v114, s93, v[64:65]
	v_mad_i32_i24 v65, v115, s93, v65
	v_lshl_add_u64 v[64:65], v[64:65], 0, v[154:155]
	s_cmp_lg_u64 s[4:5], 0
	s_cbranch_scc1 .Lwt_7
	global_store_dwordx4 v[64:65], v[108:111], off
.Lwb_7:
.LBB0_276:
	s_or_b64 exec, exec, s[82:83]
	ds_read_b32 v80, v223 offset:320
	s_mov_b32 s2, 0xbfb8aa3b
	v_readlane_b32 s0, v253, 16
	s_waitcnt lgkmcnt(0)
	v_pk_mul_f32 v[64:65], v[54:55], v[80:81] op_sel_hi:[1,0]
	v_pk_mul_f32 v[82:83], v[46:47], v[80:81] op_sel_hi:[1,0]
	v_pk_mul_f32 v[46:47], v[52:53], v[80:81] op_sel_hi:[1,0]
	v_mov_b32_dpp v52, v64 row_shr:2 row_mask:0xf bank_mask:0xf bound_ctrl:1
	v_mov_b32_dpp v53, v65 row_shr:2 row_mask:0xf bank_mask:0xf bound_ctrl:1
	v_pk_mul_f32 v[54:55], v[56:57], v[80:81] op_sel_hi:[1,0]
	v_pk_mul_f32 v[56:57], v[48:49], v[80:81] op_sel_hi:[1,0]
	v_pk_mul_f32 v[48:49], v[50:51], v[80:81] op_sel_hi:[1,0]
	v_pk_mul_f32 v[42:43], v[42:43], v[80:81] op_sel_hi:[1,0]
	v_pk_mul_f32 v[44:45], v[44:45], v[80:81] op_sel_hi:[1,0]
	v_mov_b32_dpp v50, v64 row_shr:1 row_mask:0xf bank_mask:0xf bound_ctrl:1
	v_mov_b32_dpp v51, v65 row_shr:1 row_mask:0xf bank_mask:0xf bound_ctrl:1
	v_mov_b32_dpp v52, v106 row_shl:14 row_mask:0xf bank_mask:0xf
	v_mov_b32_dpp v53, v107 row_shl:14 row_mask:0xf bank_mask:0xf
	v_mov_b32_dpp v50, v106 row_shl:15 row_mask:0xf bank_mask:0xf
	v_mov_b32_dpp v51, v107 row_shl:15 row_mask:0xf bank_mask:0xf
	v_pk_fma_f32 v[52:53], v[90:91], v[52:53], v[102:103]
	v_mov_b32_dpp v80, v54 row_shr:2 row_mask:0xf bank_mask:0xf bound_ctrl:1
	v_pk_fma_f32 v[50:51], v[94:95], v[50:51], v[52:53]
	v_mov_b32_dpp v81, v55 row_shr:2 row_mask:0xf bank_mask:0xf bound_ctrl:1
	v_pk_fma_f32 v[50:51], v[98:99], v[64:65], v[50:51]
	v_pk_mul_f32 v[52:53], v[50:51], s[2:3] op_sel_hi:[1,0]
	v_exp_f32_e32 v52, v52
	v_exp_f32_e32 v53, v53
	v_mov_b32_dpp v80, v86 row_shl:14 row_mask:0xf bank_mask:0xf
	v_mov_b32_dpp v81, v87 row_shl:14 row_mask:0xf bank_mask:0xf
	v_readlane_b32 s1, v253, 17
	v_pk_fma_f32 v[80:81], v[92:93], v[80:81], v[104:105]
	v_pk_add_f32 v[52:53], v[52:53], 1.0 op_sel_hi:[1,0]
	s_nop 0
	v_rcp_f32_e32 v52, v52
	v_rcp_f32_e32 v53, v53
	s_nop 0
	v_pk_mul_f32 v[50:51], v[50:51], v[52:53]
	s_nop 0
	v_pk_mul_f32 v[50:51], v[82:83], v[50:51]
	v_mov_b32_dpp v52, v54 row_shr:1 row_mask:0xf bank_mask:0xf bound_ctrl:1
	v_mov_b32_dpp v53, v55 row_shr:1 row_mask:0xf bank_mask:0xf bound_ctrl:1
	v_mov_b32_dpp v52, v86 row_shl:15 row_mask:0xf bank_mask:0xf
	v_mov_b32_dpp v53, v87 row_shl:15 row_mask:0xf bank_mask:0xf
	v_mov_b32_dpp v82, v78 row_shl:15 row_mask:0xf bank_mask:0xf bound_ctrl:1
	v_pk_fma_f32 v[52:53], v[96:97], v[52:53], v[80:81]
	v_mov_b32_dpp v83, v79 row_shl:15 row_mask:0xf bank_mask:0xf bound_ctrl:1
	v_pk_fma_f32 v[52:53], v[100:101], v[54:55], v[52:53]
	v_mov_b32_dpp v78, v78 row_shl:14 row_mask:0xf bank_mask:0xf bound_ctrl:1
	v_pk_mul_f32 v[80:81], v[52:53], s[2:3] op_sel_hi:[1,0]
	v_mov_b32_dpp v79, v79 row_shl:14 row_mask:0xf bank_mask:0xf bound_ctrl:1
	v_exp_f32_e32 v80, v80
	v_exp_f32_e32 v81, v81
	v_cvt_pk_bf16_f32 v50, v50, v51
	s_nop 0
	v_pk_add_f32 v[80:81], v[80:81], 1.0 op_sel_hi:[1,0]
	s_nop 0
	v_rcp_f32_e32 v80, v80
	v_rcp_f32_e32 v81, v81
	s_nop 0
	v_pk_mul_f32 v[52:53], v[52:53], v[80:81]
	v_mov_b32_dpp v80, v48 row_shr:2 row_mask:0xf bank_mask:0xf bound_ctrl:1
	v_mov_b32_dpp v81, v49 row_shr:2 row_mask:0xf bank_mask:0xf bound_ctrl:1
	v_pk_mul_f32 v[52:53], v[56:57], v[52:53]
	v_mov_b32_dpp v56, v48 row_shr:1 row_mask:0xf bank_mask:0xf bound_ctrl:1
	v_mov_b32_dpp v57, v49 row_shr:1 row_mask:0xf bank_mask:0xf bound_ctrl:1
	v_pk_add_f32 v[78:79], v[80:81], v[78:79]
	v_pk_add_f32 v[56:57], v[56:57], v[82:83]
	v_pk_fma_f32 v[78:79], v[70:71], v[78:79], v[74:75]
	v_mov_b32_dpp v80, v62 row_shl:15 row_mask:0xf bank_mask:0xf bound_ctrl:1
	v_pk_fma_f32 v[56:57], v[58:59], v[56:57], v[78:79]
	v_mov_b32_dpp v81, v63 row_shl:15 row_mask:0xf bank_mask:0xf bound_ctrl:1
	v_pk_fma_f32 v[56:57], v[66:67], v[48:49], v[56:57]
	v_mov_b32_dpp v62, v62 row_shl:14 row_mask:0xf bank_mask:0xf bound_ctrl:1
	v_pk_mul_f32 v[78:79], v[56:57], s[2:3] op_sel_hi:[1,0]
	v_mov_b32_dpp v63, v63 row_shl:14 row_mask:0xf bank_mask:0xf bound_ctrl:1
	v_exp_f32_e32 v78, v78
	v_exp_f32_e32 v79, v79
	v_add_u32_e32 v82, 16, v122
	v_cvt_pk_bf16_f32 v51, v52, v53
	v_pk_add_f32 v[78:79], v[78:79], 1.0 op_sel_hi:[1,0]
	s_nop 0
	v_rcp_f32_e32 v78, v78
	v_rcp_f32_e32 v79, v79
	s_nop 0
	v_pk_mul_f32 v[56:57], v[56:57], v[78:79]
	v_mov_b32_dpp v78, v46 row_shr:2 row_mask:0xf bank_mask:0xf bound_ctrl:1
	v_mov_b32_dpp v79, v47 row_shr:2 row_mask:0xf bank_mask:0xf bound_ctrl:1
	v_pk_mul_f32 v[42:43], v[42:43], v[56:57]
	v_mov_b32_dpp v56, v46 row_shr:1 row_mask:0xf bank_mask:0xf bound_ctrl:1
	v_mov_b32_dpp v57, v47 row_shr:1 row_mask:0xf bank_mask:0xf bound_ctrl:1
	v_pk_add_f32 v[62:63], v[78:79], v[62:63]
	v_pk_add_f32 v[56:57], v[56:57], v[80:81]
	v_pk_fma_f32 v[62:63], v[72:73], v[62:63], v[76:77]
	v_cvt_pk_bf16_f32 v52, v42, v43
	v_mov_b64_e32 v[42:43], s[0:1]
	v_pk_fma_f32 v[56:57], v[60:61], v[56:57], v[62:63]
	s_nop 0
	v_pk_fma_f32 v[56:57], v[68:69], v[46:47], v[56:57]
	s_nop 0
	v_pk_mul_f32 v[62:63], v[56:57], s[2:3] op_sel_hi:[1,0]
	s_nop 0
	v_exp_f32_e32 v62, v62
	v_exp_f32_e32 v63, v63
	s_nop 0
	v_pk_add_f32 v[62:63], v[62:63], 1.0 op_sel_hi:[1,0]
	s_nop 0
	v_rcp_f32_e32 v62, v62
	v_rcp_f32_e32 v63, v63
	s_nop 0
	v_pk_mul_f32 v[56:57], v[56:57], v[62:63]
	s_nop 0
	v_pk_mul_f32 v[44:45], v[44:45], v[56:57]
	v_cvt_pk_bf16_f32 v53, v44, v45
	v_mad_i64_i32 v[44:45], s[0:1], v82, s93, v[42:43]
	v_lshl_add_u64 v[44:45], v[44:45], 0, v[154:155]
	s_cmp_lg_u64 s[4:5], 0
	s_cbranch_scc1 .Lwt_8
	global_store_dwordx4 v[44:45], v[50:53], off
; __device__ __forceinline__ unsigned pk2(float lo, float hi) { unsigned r; asm volatile("v_cvt_pk_bf16_f32 %0, %1, %2" : "=v"(r) : "v"(lo), "v"(hi)); return r; }
; template <int CTRL> __device__ __forceinline__ float dppz(float x) { return __builtin_bit_cast(float, __builtin_amdgcn_update_dpp(0, __builtin_bit_cast(int, x), CTRL, 0xf, 0xf, true)); }
;     __device__ __forceinline__ void fast(const f32x4 (&acc)[2][2][4][2], const pg8::Unit& u, int wr, int wc, int fr, int fq, RsCache& rsc) const {
;     ...
;                 const int row = rowb + m * 16 + fr; const float s = rsc.tab[ai * 64 + m * 16 + fr]; const f32x2 s2 = (f32x2){s, s};
;                 f32x2 g[4], o[4], v[4];
; #pragma unroll
;                 for (int cp = 0; cp < 4; ++cp) { const int n = cp >> 1, e0 = (cp & 1) * 2;
;                     g[cp] = (f32x2){acc[ai][0][m][n][e0], acc[ai][0][m][n][e0 + 1]} * s2; v[cp] = (f32x2){acc[ai][1][m][n][e0], acc[ai][1][m][n][e0 + 1]} * s2; }
; #pragma unroll
;                 for (int cp = 0; cp < 4; ++cp) {
;                     f32x2 p1 = (f32x2){dppz<0x111>(g[cp].x), dppz<0x111>(g[cp].y)}, p2 = (f32x2){dppz<0x112>(g[cp].x), dppz<0x112>(g[cp].y)};
;                     if (m > 0) { p1 += (f32x2){dppz<0x10F>(gp[cp].x), dppz<0x10F>(gp[cp].y)}; p2 += (f32x2){dppz<0x10E>(gp[cp].x), dppz<0x10E>(gp[cp].y)}; }
;                     const f32x2 gv = bb[cp] + w0[cp] * p2 + w1[cp] * p1 + w2[cp] * g[cp];
;                     const f32x2 ea = gv * (-1.44269504089f);
;                     f32x2 ex; ex.x = __builtin_amdgcn_exp2f(ea.x); ex.y = __builtin_amdgcn_exp2f(ea.y);
;                     const f32x2 dn = ex + 1.0f;
;                     f32x2 rc; rc.x = __builtin_amdgcn_rcpf(dn.x); rc.y = __builtin_amdgcn_rcpf(dn.y);
;                     o[cp] = (gv * rc) * v[cp];
;                 }
;                 if (m > 0 || fr >= 2) { uint4 w; w.x = pk2(o[0].x, o[0].y); w.y = pk2(o[1].x, o[1].y); w.z = pk2(o[2].x, o[2].y); w.w = pk2(o[3].x, o[3].y); *(uint4*)(act + (size_t)row * FH + ch) = w; }
.Lwb_8:
	ds_read_b32 v50, v223 offset:384
	s_waitcnt lgkmcnt(0)
	v_pk_mul_f32 v[44:45], v[38:39], v[50:51] op_sel_hi:[1,0]
	v_pk_mul_f32 v[38:39], v[40:41], v[50:51] op_sel_hi:[1,0]
	s_nop 0
	v_mov_b32_dpp v40, v44 row_shr:2 row_mask:0xf bank_mask:0xf bound_ctrl:1
	v_mov_b32_dpp v41, v45 row_shr:2 row_mask:0xf bank_mask:0xf bound_ctrl:1
	v_pk_mul_f32 v[52:53], v[30:31], v[50:51] op_sel_hi:[1,0]
	v_pk_mul_f32 v[32:33], v[32:33], v[50:51] op_sel_hi:[1,0]
	v_pk_mul_f32 v[30:31], v[34:35], v[50:51] op_sel_hi:[1,0]
	v_pk_mul_f32 v[34:35], v[26:27], v[50:51] op_sel_hi:[1,0]
	v_pk_mul_f32 v[26:27], v[36:37], v[50:51] op_sel_hi:[1,0]
	v_pk_mul_f32 v[28:29], v[28:29], v[50:51] op_sel_hi:[1,0]
	v_mov_b32_dpp v36, v44 row_shr:1 row_mask:0xf bank_mask:0xf bound_ctrl:1
	v_mov_b32_dpp v37, v45 row_shr:1 row_mask:0xf bank_mask:0xf bound_ctrl:1
	v_mov_b32_dpp v40, v64 row_shl:14 row_mask:0xf bank_mask:0xf
	v_mov_b32_dpp v41, v65 row_shl:14 row_mask:0xf bank_mask:0xf
	v_mov_b32_dpp v36, v64 row_shl:15 row_mask:0xf bank_mask:0xf
	v_mov_b32_dpp v37, v65 row_shl:15 row_mask:0xf bank_mask:0xf
	v_pk_fma_f32 v[40:41], v[90:91], v[40:41], v[102:103]
	v_mov_b32_dpp v50, v38 row_shr:2 row_mask:0xf bank_mask:0xf bound_ctrl:1
	v_pk_fma_f32 v[36:37], v[94:95], v[36:37], v[40:41]
	v_mov_b32_dpp v51, v39 row_shr:2 row_mask:0xf bank_mask:0xf bound_ctrl:1
	v_pk_fma_f32 v[36:37], v[98:99], v[44:45], v[36:37]
	s_nop 0
	v_pk_mul_f32 v[40:41], v[36:37], s[2:3] op_sel_hi:[1,0]
	s_nop 0
	v_exp_f32_e32 v40, v40
	v_exp_f32_e32 v41, v41
	s_nop 0
	v_pk_add_f32 v[40:41], v[40:41], 1.0 op_sel_hi:[1,0]
	s_nop 0
	v_rcp_f32_e32 v40, v40
	v_rcp_f32_e32 v41, v41
	s_nop 0
	v_pk_mul_f32 v[36:37], v[36:37], v[40:41]
	s_nop 0
	v_pk_mul_f32 v[36:37], v[52:53], v[36:37]
	v_mov_b32_dpp v52, v54 row_shl:15 row_mask:0xf bank_mask:0xf bound_ctrl:1
	v_mov_b32_dpp v53, v55 row_shl:15 row_mask:0xf bank_mask:0xf bound_ctrl:1
	v_mov_b32_dpp v40, v38 row_shr:1 row_mask:0xf bank_mask:0xf bound_ctrl:1
	v_mov_b32_dpp v41, v39 row_shr:1 row_mask:0xf bank_mask:0xf bound_ctrl:1
	v_mov_b32_dpp v50, v54 row_shl:14 row_mask:0xf bank_mask:0xf
	v_mov_b32_dpp v51, v55 row_shl:14 row_mask:0xf bank_mask:0xf
	v_pk_add_f32 v[40:41], v[40:41], v[52:53]
	v_pk_fma_f32 v[50:51], v[92:93], v[50:51], v[104:105]
	v_mov_b32_dpp v52, v48 row_shl:15 row_mask:0xf bank_mask:0xf bound_ctrl:1
	v_pk_fma_f32 v[40:41], v[96:97], v[40:41], v[50:51]
	v_mov_b32_dpp v53, v49 row_shl:15 row_mask:0xf bank_mask:0xf bound_ctrl:1
	v_pk_fma_f32 v[40:41], v[100:101], v[38:39], v[40:41]
	v_mov_b32_dpp v48, v48 row_shl:14 row_mask:0xf bank_mask:0xf bound_ctrl:1
	v_pk_mul_f32 v[50:51], v[40:41], s[2:3] op_sel_hi:[1,0]
	v_mov_b32_dpp v49, v49 row_shl:14 row_mask:0xf bank_mask:0xf bound_ctrl:1
	v_exp_f32_e32 v50, v50
	v_exp_f32_e32 v51, v51
	s_nop 0
	v_pk_add_f32 v[50:51], v[50:51], 1.0 op_sel_hi:[1,0]
	s_nop 0
	v_rcp_f32_e32 v50, v50
	v_rcp_f32_e32 v51, v51
	s_nop 0
	v_pk_mul_f32 v[40:41], v[40:41], v[50:51]
	v_mov_b32_dpp v50, v30 row_shr:2 row_mask:0xf bank_mask:0xf bound_ctrl:1
	v_mov_b32_dpp v51, v31 row_shr:2 row_mask:0xf bank_mask:0xf bound_ctrl:1
	v_pk_mul_f32 v[40:41], v[32:33], v[40:41]
	v_mov_b32_dpp v32, v30 row_shr:1 row_mask:0xf bank_mask:0xf bound_ctrl:1
	v_mov_b32_dpp v33, v31 row_shr:1 row_mask:0xf bank_mask:0xf bound_ctrl:1
	v_pk_add_f32 v[48:49], v[50:51], v[48:49]
	v_pk_add_f32 v[32:33], v[32:33], v[52:53]
	v_pk_fma_f32 v[48:49], v[70:71], v[48:49], v[74:75]
	v_mov_b32_dpp v50, v46 row_shl:15 row_mask:0xf bank_mask:0xf bound_ctrl:1
	v_pk_fma_f32 v[32:33], v[58:59], v[32:33], v[48:49]
	v_mov_b32_dpp v51, v47 row_shl:15 row_mask:0xf bank_mask:0xf bound_ctrl:1
	v_pk_fma_f32 v[32:33], v[66:67], v[30:31], v[32:33]
	v_mov_b32_dpp v46, v46 row_shl:14 row_mask:0xf bank_mask:0xf bound_ctrl:1
	v_pk_mul_f32 v[48:49], v[32:33], s[2:3] op_sel_hi:[1,0]
	v_mov_b32_dpp v47, v47 row_shl:14 row_mask:0xf bank_mask:0xf bound_ctrl:1
	v_exp_f32_e32 v48, v48
	v_exp_f32_e32 v49, v49
	v_add_u32_e32 v52, 32, v122
	v_pk_add_f32 v[48:49], v[48:49], 1.0 op_sel_hi:[1,0]
	s_nop 0
	v_rcp_f32_e32 v48, v48
	v_rcp_f32_e32 v49, v49
	s_nop 0
	v_pk_mul_f32 v[32:33], v[32:33], v[48:49]
	v_mov_b32_dpp v48, v26 row_shr:2 row_mask:0xf bank_mask:0xf bound_ctrl:1
	v_mov_b32_dpp v49, v27 row_shr:2 row_mask:0xf bank_mask:0xf bound_ctrl:1
	v_pk_mul_f32 v[34:35], v[34:35], v[32:33]
	v_mov_b32_dpp v32, v26 row_shr:1 row_mask:0xf bank_mask:0xf bound_ctrl:1
	v_mov_b32_dpp v33, v27 row_shr:1 row_mask:0xf bank_mask:0xf bound_ctrl:1
	v_pk_add_f32 v[46:47], v[48:49], v[46:47]
	v_pk_add_f32 v[32:33], v[32:33], v[50:51]
	v_pk_fma_f32 v[46:47], v[72:73], v[46:47], v[76:77]
	s_nop 0
	v_pk_fma_f32 v[32:33], v[60:61], v[32:33], v[46:47]
	s_nop 0
	v_pk_fma_f32 v[32:33], v[68:69], v[26:27], v[32:33]
	s_nop 0
	v_pk_mul_f32 v[46:47], v[32:33], s[2:3] op_sel_hi:[1,0]
	s_nop 0
	v_exp_f32_e32 v46, v46
	v_exp_f32_e32 v47, v47
	s_nop 0
	v_pk_add_f32 v[46:47], v[46:47], 1.0 op_sel_hi:[1,0]
	s_nop 0
	v_rcp_f32_e32 v46, v46
	v_rcp_f32_e32 v47, v47
	s_nop 0
	v_pk_mul_f32 v[32:33], v[32:33], v[46:47]
	s_nop 0
	v_pk_mul_f32 v[28:29], v[28:29], v[32:33]
	v_cvt_pk_bf16_f32 v32, v36, v37
	v_cvt_pk_bf16_f32 v33, v40, v41
	v_cvt_pk_bf16_f32 v34, v34, v35
	v_cvt_pk_bf16_f32 v35, v28, v29
	v_mad_i64_i32 v[28:29], s[0:1], v52, s93, v[42:43]
	v_lshl_add_u64 v[28:29], v[28:29], 0, v[154:155]
	s_cmp_lg_u64 s[4:5], 0
	s_cbranch_scc1 .Lwt_9
	global_store_dwordx4 v[28:29], v[32:35], off

; __device__ __forceinline__ unsigned pk2(float lo, float hi) { unsigned r; asm volatile("v_cvt_pk_bf16_f32 %0, %1, %2" : "=v"(r) : "v"(lo), "v"(hi)); return r; }
;     __device__ __forceinline__ void fast(const f32x4 (&acc)[2][2][4][2], const pg8::Unit& u, int wr, int wc, int fr, int fq, RsCache& rsc) const {
;     ...
;                 if (m > 0 || fr >= 2) { uint4 w; w.x = pk2(o[0].x, o[0].y); w.y = pk2(o[1].x, o[1].y); w.z = pk2(o[2].x, o[2].y); w.w = pk2(o[3].x, o[3].y); *(uint4*)(act + (size_t)row * FH + ch) = w; }
;                 if (m == 0 && fr < 2) { uint4 w; w.x = pk2(g[0].x, g[0].y); w.y = pk2(g[1].x, g[1].y); w.z = pk2(g[2].x, g[2].y); w.w = pk2(g[3].x, g[3].y); *(uint4*)(sideg + ((size_t)blk * 4 + fr) * FH + ch) = w;
;                     uint4 q; q.x = pk2(v[0].x, v[0].y); q.y = pk2(v[1].x, v[1].y); q.z = pk2(v[2].x, v[2].y); q.w = pk2(v[3].x, v[3].y); *(uint4*)(sidev + ((size_t)blk * 2 + fr) * FH + ch) = q; }
;                 if (m == 3 && fr >= 14) { uint4 w; w.x = pk2(g[0].x, g[0].y); w.y = pk2(g[1].x, g[1].y); w.z = pk2(g[2].x, g[2].y); w.w = pk2(g[3].x, g[3].y); *(uint4*)(sideg + ((size_t)blk * 4 + 2 + (fr - 14)) * FH + ch) = w; }
.Lwt_1:
	global_store_dwordx4 v[140:141], v[146:149], off sc1
	s_branch .Lwb_1
.Lwt_2:
	global_store_dwordx4 v[124:125], v[128:131], off sc1
	s_branch .Lwb_2
.Lwt_3:
	global_store_dwordx4 v[108:109], v[114:117], off sc1
	s_branch .Lwb_3
.Lwt_4:
	global_store_dwordx4 v[106:107], v[108:111], off sc1
	s_branch .Lwb_4
.Lwt_5:
	global_store_dwordx4 v[84:85], v[110:113], off sc1
	s_branch .Lwb_5

; __device__ __forceinline__ unsigned pk2(float lo, float hi) { unsigned r; asm volatile("v_cvt_pk_bf16_f32 %0, %1, %2" : "=v"(r) : "v"(lo), "v"(hi)); return r; }
;     __device__ __forceinline__ void fast(const f32x4 (&acc)[2][2][4][2], const pg8::Unit& u, int wr, int wc, int fr, int fq, RsCache& rsc) const {
;     ...
;                 if (m > 0 || fr >= 2) { uint4 w; w.x = pk2(o[0].x, o[0].y); w.y = pk2(o[1].x, o[1].y); w.z = pk2(o[2].x, o[2].y); w.w = pk2(o[3].x, o[3].y); *(uint4*)(act + (size_t)row * FH + ch) = w; }
;                 if (m == 0 && fr < 2) { uint4 w; w.x = pk2(g[0].x, g[0].y); w.y = pk2(g[1].x, g[1].y); w.z = pk2(g[2].x, g[2].y); w.w = pk2(g[3].x, g[3].y); *(uint4*)(sideg + ((size_t)blk * 4 + fr) * FH + ch) = w;
;                     uint4 q; q.x = pk2(v[0].x, v[0].y); q.y = pk2(v[1].x, v[1].y); q.z = pk2(v[2].x, v[2].y); q.w = pk2(v[3].x, v[3].y); *(uint4*)(sidev + ((size_t)blk * 2 + fr) * FH + ch) = q; }
;                 if (m == 3 && fr >= 14) { uint4 w; w.x = pk2(g[0].x, g[0].y); w.y = pk2(g[1].x, g[1].y); w.z = pk2(g[2].x, g[2].y); w.w = pk2(g[3].x, g[3].y); *(uint4*)(sideg + ((size_t)blk * 4 + 2 + (fr - 14)) * FH + ch) = w; }
.Lwt_7:
	global_store_dwordx4 v[64:65], v[108:111], off sc1
	s_branch .Lwb_7
.Lwt_8:
	global_store_dwordx4 v[44:45], v[50:53], off sc1
	s_branch .Lwb_8
